# EpiBranch::mid (P9): ten later gate loads issued together with the first eight via SGPR-base addressing into free VGPRs; waits re-derived
# baseline (speedup 1.0000x reference)
; __device__ __forceinline__ float rcp_f(float x) { return __builtin_amdgcn_rcpf(x); }
;     __device__ __forceinline__ void mid(AccT& acc, const pg8::Unit& u, int wr, int wc, int fr, int fq) const {
; #pragma unroll
;         for (int ai = 0; ai < 2; ++ai)
; #pragma unroll
;             for (int m = 0; m < 4; ++m) { int row = u.pm * 256 + ai * 128 + wr * 64 + m * 16 + fr; if (row >= M) row = M - 1;
; #pragma unroll
;                 for (int bj = 0; bj < 2; ++bj) { const size_t o = (size_t)row * D + u.pn * 256 + bj * 128 + wc * 32 + 8 * fq;
;                     const u32x4 a = *(const u32x4*)(mga + o), b = *(const u32x4*)(mgb + o);
;                     f32x4 r0, r1;
;                     r0[0] = bflo(a.x) * rcp_f(bflo(b.x)); r0[1] = bfhi(a.x) * rcp_f(bfhi(b.x)); r0[2] = bflo(a.y) * rcp_f(bflo(b.y)); r0[3] = bfhi(a.y) * rcp_f(bfhi(b.y));
;                     r1[0] = bflo(a.z) * rcp_f(bflo(b.z)); r1[1] = bfhi(a.z) * rcp_f(bfhi(b.z)); r1[2] = bflo(a.w) * rcp_f(bflo(b.w)); r1[3] = bfhi(a.w) * rcp_f(bfhi(b.w));
;                     acc[ai][bj][m][0] = acc[ai][bj][m][0] * r0; acc[ai][bj][m][1] = acc[ai][bj][m][1] * r1; } }
;     }
.LBB0_1930:
	v_min_i32_e32 v2, 0x407f, v2
	v_ashrrev_i32_e32 v3, 31, v2
	v_lshlrev_b64 v[2:3], 10, v[2:3]
	s_lshl_b32 s38, s6, 8
	v_lshl_add_u64 v[2:3], v[2:3], 0, v[154:155]
	s_ashr_i32 s39, s38, 31
	v_lshl_add_u64 v[132:133], v[2:3], 0, s[38:39]
	s_or_b32 s6, s38, 0x80
	s_mov_b32 s7, s39
	v_lshlrev_b64 v[132:133], 1, v[132:133]
	v_lshl_add_u64 v[2:3], v[2:3], 0, s[6:7]
	v_lshl_add_u64 v[134:135], s[10:11], 0, v[132:133]
	v_lshl_add_u64 v[132:133], s[92:93], 0, v[132:133]
	v_lshlrev_b64 v[2:3], 1, v[2:3]
	global_load_dwordx4 v[140:143], v[134:135], off
	global_load_dwordx4 v[176:179], v[132:133], off
	v_lshl_add_u64 v[132:133], s[10:11], 0, v[2:3]
	v_lshl_add_u64 v[2:3], s[92:93], 0, v[2:3]
	v_add_u32_e32 v1, s27, v168
	global_load_dwordx4 v[180:183], v[132:133], off
	global_load_dwordx4 v[184:187], v[2:3], off
	v_min_i32_e32 v2, 0x407f, v1
	v_ashrrev_i32_e32 v3, 31, v2
	v_lshlrev_b64 v[2:3], 10, v[2:3]
	v_lshl_add_u64 v[2:3], v[2:3], 0, v[154:155]
	v_lshl_add_u64 v[132:133], v[2:3], 0, s[38:39]
	v_lshlrev_b64 v[132:133], 1, v[132:133]
	v_lshl_add_u64 v[134:135], s[10:11], 0, v[132:133]
	global_load_dwordx4 v[188:191], v[134:135], off
	v_lshl_add_u64 v[132:133], s[92:93], 0, v[132:133]
	global_load_dwordx4 v[192:195], v[132:133], off
	v_lshl_add_u64 v[2:3], v[2:3], 0, s[6:7]
	v_lshlrev_b64 v[2:3], 1, v[2:3]
	v_lshl_add_u64 v[132:133], s[92:93], 0, v[2:3]
	v_lshl_add_u64 v[2:3], s[10:11], 0, v[2:3]
	global_load_dwordx4 v[132:135], v[132:133], off
	s_nop 0
	global_load_dwordx4 v[136:139], v[2:3], off
	v_add_u32_e32 v210, s27, v169
	v_min_i32_e32 v210, 0x407f, v210
	v_lshlrev_b32_e32 v210, 10, v210
	v_add3_u32 v210, v210, v154, s38
	v_lshlrev_b32_e32 v210, 1, v210
	v_add_u32_e32 v211, s27, v170
	v_min_i32_e32 v211, 0x407f, v211
	v_lshlrev_b32_e32 v211, 10, v211
	v_add3_u32 v211, v211, v154, s38
	v_lshlrev_b32_e32 v211, 1, v211
	v_add_u32_e32 v236, s27, v171
	v_min_i32_e32 v236, 0x407f, v236
	v_lshlrev_b32_e32 v236, 10, v236
	v_add3_u32 v236, v236, v154, s38
	v_lshlrev_b32_e32 v236, 1, v236
	global_load_dwordx4 v[212:215], v210, s[92:93]
	global_load_dwordx4 v[216:219], v210, s[10:11]
	global_load_dwordx4 v[220:223], v210, s[92:93] offset:256
	global_load_dwordx4 v[224:227], v210, s[10:11] offset:256
	global_load_dwordx4 v[228:231], v211, s[92:93]
	global_load_dwordx4 v[232:235], v211, s[10:11]
	global_load_dwordx4 v[240:243], v211, s[92:93] offset:256
	global_load_dwordx4 v[244:247], v211, s[10:11] offset:256
	global_load_dwordx4 v[248:251], v236, s[92:93]
	global_load_dwordx4 v[252:255], v236, s[10:11]
	s_waitcnt vmcnt(17)
	v_lshlrev_b32_e32 v1, 16, v140
	v_and_b32_e32 v196, 0xffff0000, v140
	s_waitcnt vmcnt(16)
	v_lshlrev_b32_e32 v2, 16, v176
	v_and_b32_e32 v3, 0xffff0000, v176
	v_lshlrev_b32_e32 v197, 16, v141
	v_and_b32_e32 v198, 0xffff0000, v141
	v_lshlrev_b32_e32 v140, 16, v177
	v_and_b32_e32 v141, 0xffff0000, v177
	v_lshlrev_b32_e32 v199, 16, v142
	v_and_b32_e32 v200, 0xffff0000, v142
	v_lshlrev_b32_e32 v176, 16, v178
	v_and_b32_e32 v177, 0xffff0000, v178
	v_lshlrev_b32_e32 v201, 16, v143
	v_and_b32_e32 v202, 0xffff0000, v143
	v_lshlrev_b32_e32 v142, 16, v179
	v_and_b32_e32 v143, 0xffff0000, v179
	s_waitcnt vmcnt(15)
	v_lshlrev_b32_e32 v203, 16, v180
	v_and_b32_e32 v204, 0xffff0000, v180
	s_waitcnt vmcnt(14)
	v_lshlrev_b32_e32 v178, 16, v184
	v_and_b32_e32 v179, 0xffff0000, v184
	v_lshlrev_b32_e32 v205, 16, v181
	v_and_b32_e32 v206, 0xffff0000, v181
	v_lshlrev_b32_e32 v180, 16, v185
	v_and_b32_e32 v181, 0xffff0000, v185
	v_lshlrev_b32_e32 v207, 16, v182
	v_and_b32_e32 v208, 0xffff0000, v182
	v_lshlrev_b32_e32 v184, 16, v186
	v_and_b32_e32 v185, 0xffff0000, v186
	v_lshlrev_b32_e32 v186, 16, v183
	v_and_b32_e32 v209, 0xffff0000, v183
	v_rcp_f32_e32 v182, v1
	v_rcp_f32_e32 v183, v196
	v_rcp_f32_e32 v196, v197
	v_rcp_f32_e32 v197, v198
	v_rcp_f32_e32 v198, v199
	v_rcp_f32_e32 v199, v200
	v_rcp_f32_e32 v200, v201
	v_rcp_f32_e32 v201, v202
	v_rcp_f32_e32 v202, v203
	v_rcp_f32_e32 v203, v204
	v_rcp_f32_e32 v204, v205
	v_rcp_f32_e32 v205, v206
	v_rcp_f32_e32 v206, v207
	v_rcp_f32_e32 v207, v208
	v_rcp_f32_e32 v208, v186
	v_rcp_f32_e32 v209, v209
	v_pk_mul_f32 v[2:3], v[182:183], v[2:3]
	s_waitcnt vmcnt(13)
	v_lshlrev_b32_e32 v1, 16, v188
	v_pk_mul_f32 v[128:129], v[128:129], v[2:3]
	v_lshlrev_b32_e32 v2, 16, v187
	v_and_b32_e32 v3, 0xffff0000, v187
	v_pk_mul_f32 v[2:3], v[208:209], v[2:3]
	v_pk_mul_f32 v[140:141], v[196:197], v[140:141]
	v_pk_mul_f32 v[94:95], v[94:95], v[2:3]
	v_rcp_f32_e32 v2, v1
	v_add_u32_e32 v1, s27, v169
	v_pk_mul_f32 v[130:131], v[130:131], v[140:141]
	v_min_i32_e32 v140, 0x407f, v1
	v_ashrrev_i32_e32 v141, 31, v140
	v_pk_mul_f32 v[180:181], v[204:205], v[180:181]
	v_lshlrev_b64 v[140:141], 10, v[140:141]
	v_pk_mul_f32 v[98:99], v[98:99], v[180:181]
	v_lshl_add_u64 v[180:181], v[140:141], 0, v[154:155]
	v_lshl_add_u64 v[140:141], v[180:181], 0, s[38:39]
	v_pk_mul_f32 v[176:177], v[198:199], v[176:177]
	v_pk_mul_f32 v[142:143], v[200:201], v[142:143]
	v_lshlrev_b64 v[140:141], 1, v[140:141]
	v_pk_mul_f32 v[178:179], v[202:203], v[178:179]
	v_pk_mul_f32 v[126:127], v[126:127], v[142:143]
	v_pk_mul_f32 v[124:125], v[124:125], v[176:177]
	v_lshl_add_u64 v[142:143], s[92:93], 0, v[140:141]
	v_lshl_add_u64 v[176:177], s[10:11], 0, v[140:141]
	v_pk_mul_f32 v[96:97], v[96:97], v[178:179]
	s_nop 0
	v_and_b32_e32 v1, 0xffff0000, v188
	v_rcp_f32_e32 v3, v1
	v_lshlrev_b32_e32 v1, 16, v189
	v_pk_mul_f32 v[182:183], v[206:207], v[184:185]
	v_rcp_f32_e32 v184, v1
	v_and_b32_e32 v1, 0xffff0000, v189
	v_rcp_f32_e32 v185, v1
	v_pk_mul_f32 v[92:93], v[92:93], v[182:183]
	s_waitcnt vmcnt(12)
; __device__ __forceinline__ float rcp_f(float x) { return __builtin_amdgcn_rcpf(x); }
;     __device__ __forceinline__ void mid(AccT& acc, const pg8::Unit& u, int wr, int wc, int fr, int fq) const {
; #pragma unroll
;         for (int ai = 0; ai < 2; ++ai)
; #pragma unroll
;             for (int m = 0; m < 4; ++m) { int row = u.pm * 256 + ai * 128 + wr * 64 + m * 16 + fr; if (row >= M) row = M - 1;
; #pragma unroll
;                 for (int bj = 0; bj < 2; ++bj) { const size_t o = (size_t)row * D + u.pn * 256 + bj * 128 + wc * 32 + 8 * fq;
;                     const u32x4 a = *(const u32x4*)(mga + o), b = *(const u32x4*)(mgb + o);
;                     f32x4 r0, r1;
;                     r0[0] = bflo(a.x) * rcp_f(bflo(b.x)); r0[1] = bfhi(a.x) * rcp_f(bfhi(b.x)); r0[2] = bflo(a.y) * rcp_f(bflo(b.y)); r0[3] = bfhi(a.y) * rcp_f(bfhi(b.y));
;                     r1[0] = bflo(a.z) * rcp_f(bflo(b.z)); r1[1] = bfhi(a.z) * rcp_f(bfhi(b.z)); r1[2] = bflo(a.w) * rcp_f(bflo(b.w)); r1[3] = bfhi(a.w) * rcp_f(bfhi(b.w));
;                     acc[ai][bj][m][0] = acc[ai][bj][m][0] * r0; acc[ai][bj][m][1] = acc[ai][bj][m][1] * r1; } }
;     }
	v_lshlrev_b32_e32 v182, 16, v192
	v_and_b32_e32 v183, 0xffff0000, v192
	v_pk_mul_f32 v[2:3], v[2:3], v[182:183]
	v_lshlrev_b32_e32 v182, 16, v193
	v_and_b32_e32 v183, 0xffff0000, v193
	v_lshlrev_b32_e32 v1, 16, v190
	v_pk_mul_f32 v[182:183], v[184:185], v[182:183]
	v_rcp_f32_e32 v184, v1
	v_and_b32_e32 v1, 0xffff0000, v190
	v_rcp_f32_e32 v185, v1
	v_lshlrev_b32_e32 v1, 16, v191
	v_rcp_f32_e32 v188, v1
	v_and_b32_e32 v1, 0xffff0000, v191
	v_rcp_f32_e32 v189, v1
	s_waitcnt vmcnt(10)
	v_lshlrev_b32_e32 v1, 16, v136
	v_lshlrev_b32_e32 v186, 16, v194
	v_and_b32_e32 v187, 0xffff0000, v194
	v_pk_mul_f32 v[120:121], v[120:121], v[2:3]
	v_rcp_f32_e32 v2, v1
	v_lshl_add_u64 v[180:181], v[180:181], 0, s[6:7]
	v_and_b32_e32 v1, 0xffff0000, v136
	v_pk_mul_f32 v[184:185], v[184:185], v[186:187]
	v_lshlrev_b32_e32 v186, 16, v195
	v_and_b32_e32 v187, 0xffff0000, v195
	v_lshlrev_b64 v[180:181], 1, v[180:181]
	v_rcp_f32_e32 v3, v1
	v_lshlrev_b32_e32 v1, 16, v137
	v_pk_mul_f32 v[186:187], v[188:189], v[186:187]
	v_pk_mul_f32 v[122:123], v[122:123], v[182:183]
	v_pk_mul_f32 v[116:117], v[116:117], v[184:185]
	v_lshl_add_u64 v[182:183], s[92:93], 0, v[180:181]
	v_lshl_add_u64 v[184:185], s[10:11], 0, v[180:181]
	v_rcp_f32_e32 v136, v1
	v_and_b32_e32 v1, 0xffff0000, v137
	v_pk_mul_f32 v[118:119], v[118:119], v[186:187]
	s_nop 0
	v_rcp_f32_e32 v137, v1
	v_lshlrev_b32_e32 v188, 16, v132
	v_and_b32_e32 v189, 0xffff0000, v132
	v_lshlrev_b32_e32 v132, 16, v133
	v_and_b32_e32 v133, 0xffff0000, v133
	v_lshlrev_b32_e32 v194, 16, v134
	v_and_b32_e32 v195, 0xffff0000, v134
	v_add_u32_e32 v134, s27, v170
	v_pk_mul_f32 v[132:133], v[136:137], v[132:133]
	v_min_i32_e32 v136, 0x407f, v134
	v_ashrrev_i32_e32 v137, 31, v136
	v_lshlrev_b64 v[136:137], 10, v[136:137]
	v_lshlrev_b32_e32 v1, 16, v138
	v_lshl_add_u64 v[198:199], v[136:137], 0, v[154:155]
	v_rcp_f32_e32 v192, v1
	v_and_b32_e32 v1, 0xffff0000, v138
	v_lshl_add_u64 v[136:137], v[198:199], 0, s[38:39]
	v_rcp_f32_e32 v193, v1
	v_lshlrev_b32_e32 v1, 16, v139
	v_lshlrev_b64 v[136:137], 1, v[136:137]
	v_pk_mul_f32 v[2:3], v[2:3], v[188:189]
	v_rcp_f32_e32 v196, v1
	v_and_b32_e32 v1, 0xffff0000, v139
	v_lshl_add_u64 v[138:139], s[92:93], 0, v[136:137]
	v_lshl_add_u64 v[188:189], s[10:11], 0, v[136:137]
	s_nop 0
	v_rcp_f32_e32 v197, v1
	v_lshlrev_b32_e32 v134, 16, v135
	v_and_b32_e32 v135, 0xffff0000, v135
	v_pk_mul_f32 v[88:89], v[88:89], v[2:3]
	v_pk_mul_f32 v[134:135], v[196:197], v[134:135]
	v_pk_mul_f32 v[90:91], v[90:91], v[132:133]
	v_pk_mul_f32 v[86:87], v[86:87], v[134:135]
	v_pk_mul_f32 v[192:193], v[192:193], v[194:195]
	s_waitcnt vmcnt(9)
	v_lshlrev_b32_e32 v132, 16, v212
	s_waitcnt vmcnt(8)
	v_lshlrev_b32_e32 v1, 16, v216
	v_rcp_f32_e32 v2, v1
	v_and_b32_e32 v1, 0xffff0000, v216
	v_rcp_f32_e32 v3, v1
	v_lshlrev_b32_e32 v1, 16, v217
	v_rcp_f32_e32 v134, v1
	v_and_b32_e32 v1, 0xffff0000, v217
	v_rcp_f32_e32 v135, v1
	v_and_b32_e32 v133, 0xffff0000, v212
	v_pk_mul_f32 v[2:3], v[2:3], v[132:133]
	v_lshlrev_b32_e32 v132, 16, v213
	v_and_b32_e32 v133, 0xffff0000, v213
	v_lshlrev_b32_e32 v1, 16, v218
	v_pk_mul_f32 v[176:177], v[134:135], v[132:133]
	v_rcp_f32_e32 v132, v1
	v_and_b32_e32 v1, 0xffff0000, v218
	v_rcp_f32_e32 v133, v1
	v_lshlrev_b32_e32 v1, 16, v219
	v_rcp_f32_e32 v140, v1
	v_and_b32_e32 v1, 0xffff0000, v219
	v_rcp_f32_e32 v141, v1
	v_lshlrev_b32_e32 v134, 16, v214
	v_and_b32_e32 v135, 0xffff0000, v214
	v_pk_mul_f32 v[178:179], v[132:133], v[134:135]
	v_lshlrev_b32_e32 v132, 16, v215
	v_and_b32_e32 v133, 0xffff0000, v215
	v_pk_mul_f32 v[84:85], v[84:85], v[192:193]
	v_pk_mul_f32 v[192:193], v[140:141], v[132:133]
	v_lshl_add_u64 v[132:133], v[198:199], 0, s[6:7]
	v_lshlrev_b64 v[132:133], 1, v[132:133]
	v_lshl_add_u64 v[134:135], s[92:93], 0, v[132:133]
	v_lshl_add_u64 v[140:141], s[10:11], 0, v[132:133]
	s_nop 0
	v_pk_mul_f32 v[112:113], v[112:113], v[2:3]
	v_pk_mul_f32 v[108:109], v[108:109], v[178:179]
	v_pk_mul_f32 v[114:115], v[114:115], v[176:177]
	v_pk_mul_f32 v[110:111], v[110:111], v[192:193]
	s_waitcnt vmcnt(7)
	v_lshlrev_b32_e32 v176, 16, v220
	s_waitcnt vmcnt(6)
	v_lshlrev_b32_e32 v1, 16, v224
	v_rcp_f32_e32 v2, v1
	v_and_b32_e32 v1, 0xffff0000, v224
	v_rcp_f32_e32 v3, v1
	v_lshlrev_b32_e32 v1, 16, v225
	v_rcp_f32_e32 v178, v1
	v_and_b32_e32 v1, 0xffff0000, v225
	v_rcp_f32_e32 v179, v1
	v_and_b32_e32 v177, 0xffff0000, v220
	v_pk_mul_f32 v[2:3], v[2:3], v[176:177]
	v_lshlrev_b32_e32 v176, 16, v221
	v_and_b32_e32 v177, 0xffff0000, v221
	v_lshlrev_b32_e32 v1, 16, v226
	v_pk_mul_f32 v[176:177], v[178:179], v[176:177]
	v_rcp_f32_e32 v178, v1
	v_and_b32_e32 v1, 0xffff0000, v226
	v_rcp_f32_e32 v179, v1
	v_lshlrev_b32_e32 v1, 16, v227
	v_rcp_f32_e32 v184, v1
	v_and_b32_e32 v1, 0xffff0000, v227
	v_rcp_f32_e32 v185, v1
	v_pk_mul_f32 v[80:81], v[80:81], v[2:3]
	v_pk_mul_f32 v[82:83], v[82:83], v[176:177]
	v_lshlrev_b32_e32 v180, 16, v222
	v_and_b32_e32 v181, 0xffff0000, v222
	v_pk_mul_f32 v[178:179], v[178:179], v[180:181]
	s_waitcnt vmcnt(4)
; __device__ __forceinline__ float rcp_f(float x) { return __builtin_amdgcn_rcpf(x); }
;     __device__ __forceinline__ void mid(AccT& acc, const pg8::Unit& u, int wr, int wc, int fr, int fq) const {
; #pragma unroll
;         for (int ai = 0; ai < 2; ++ai)
; #pragma unroll
;             for (int m = 0; m < 4; ++m) { int row = u.pm * 256 + ai * 128 + wr * 64 + m * 16 + fr; if (row >= M) row = M - 1;
; #pragma unroll
;                 for (int bj = 0; bj < 2; ++bj) { const size_t o = (size_t)row * D + u.pn * 256 + bj * 128 + wc * 32 + 8 * fq;
;                     const u32x4 a = *(const u32x4*)(mga + o), b = *(const u32x4*)(mgb + o);
;                     f32x4 r0, r1;
;                     r0[0] = bflo(a.x) * rcp_f(bflo(b.x)); r0[1] = bfhi(a.x) * rcp_f(bfhi(b.x)); r0[2] = bflo(a.y) * rcp_f(bflo(b.y)); r0[3] = bfhi(a.y) * rcp_f(bfhi(b.y));
;                     r1[0] = bflo(a.z) * rcp_f(bflo(b.z)); r1[1] = bfhi(a.z) * rcp_f(bfhi(b.z)); r1[2] = bflo(a.w) * rcp_f(bflo(b.w)); r1[3] = bfhi(a.w) * rcp_f(bfhi(b.w));
;                     acc[ai][bj][m][0] = acc[ai][bj][m][0] * r0; acc[ai][bj][m][1] = acc[ai][bj][m][1] * r1; } }
;     }
	v_lshlrev_b32_e32 v1, 16, v232
	v_rcp_f32_e32 v2, v1
	v_add_u32_e32 v1, s27, v171
	v_min_i32_e32 v176, 0x407f, v1
	v_ashrrev_i32_e32 v177, 31, v176
	v_lshlrev_b32_e32 v180, 16, v223
	v_and_b32_e32 v181, 0xffff0000, v223
	v_lshlrev_b64 v[176:177], 10, v[176:177]
	v_pk_mul_f32 v[180:181], v[184:185], v[180:181]
	v_lshl_add_u64 v[184:185], v[176:177], 0, v[154:155]
	v_lshl_add_u64 v[176:177], v[184:185], 0, s[38:39]
	v_lshlrev_b64 v[176:177], 1, v[176:177]
	v_pk_mul_f32 v[78:79], v[78:79], v[180:181]
	v_pk_mul_f32 v[76:77], v[76:77], v[178:179]
	v_lshl_add_u64 v[178:179], s[92:93], 0, v[176:177]
	v_lshl_add_u64 v[180:181], s[10:11], 0, v[176:177]
	s_nop 0
	v_and_b32_e32 v1, 0xffff0000, v232
	v_rcp_f32_e32 v3, v1
	v_lshlrev_b32_e32 v1, 16, v233
	v_rcp_f32_e32 v188, v1
	v_and_b32_e32 v1, 0xffff0000, v233
	v_lshlrev_b32_e32 v186, 16, v228
	v_and_b32_e32 v187, 0xffff0000, v228
	v_rcp_f32_e32 v189, v1
	v_lshlrev_b32_e32 v1, 16, v234
	v_pk_mul_f32 v[2:3], v[2:3], v[186:187]
	v_rcp_f32_e32 v186, v1
	v_and_b32_e32 v1, 0xffff0000, v234
	v_rcp_f32_e32 v187, v1
	v_lshlrev_b32_e32 v1, 16, v235
	v_rcp_f32_e32 v190, v1
	v_and_b32_e32 v1, 0xffff0000, v235
	v_rcp_f32_e32 v191, v1
	v_lshlrev_b32_e32 v136, 16, v229
	v_and_b32_e32 v137, 0xffff0000, v229
	v_pk_mul_f32 v[136:137], v[188:189], v[136:137]
	v_lshlrev_b32_e32 v188, 16, v230
	v_and_b32_e32 v189, 0xffff0000, v230
	v_lshlrev_b32_e32 v138, 16, v231
	v_and_b32_e32 v139, 0xffff0000, v231
	v_pk_mul_f32 v[106:107], v[106:107], v[136:137]
	s_waitcnt vmcnt(2)
	v_lshlrev_b32_e32 v1, 16, v244
	v_pk_mul_f32 v[104:105], v[104:105], v[2:3]
	v_rcp_f32_e32 v2, v1
	v_lshl_add_u64 v[136:137], v[184:185], 0, s[6:7]
	v_and_b32_e32 v1, 0xffff0000, v244
	v_pk_mul_f32 v[138:139], v[190:191], v[138:139]
	v_lshlrev_b64 v[136:137], 1, v[136:137]
	v_rcp_f32_e32 v3, v1
	v_pk_mul_f32 v[186:187], v[186:187], v[188:189]
	v_pk_mul_f32 v[102:103], v[102:103], v[138:139]
	v_lshl_add_u64 v[138:139], s[92:93], 0, v[136:137]
	v_lshl_add_u64 v[184:185], s[10:11], 0, v[136:137]
	v_pk_mul_f32 v[100:101], v[100:101], v[186:187]
	global_load_dwordx4 v[136:139], v[138:139], off
	s_nop 0
	global_load_dwordx4 v[184:187], v[184:185], off
	v_lshlrev_b32_e32 v188, 16, v240
	v_and_b32_e32 v189, 0xffff0000, v240
	v_lshlrev_b32_e32 v196, 16, v242
	v_and_b32_e32 v197, 0xffff0000, v242
	v_add_u32_e32 v134, s27, v172
	v_pk_mul_f32 v[2:3], v[2:3], v[188:189]
	v_min_i32_e32 v188, 0x407f, v134
	v_ashrrev_i32_e32 v189, 31, v188
	v_lshlrev_b64 v[188:189], 10, v[188:189]
	v_lshl_add_u64 v[198:199], v[188:189], 0, v[154:155]
	v_lshl_add_u64 v[188:189], v[198:199], 0, s[38:39]
	v_lshlrev_b64 v[188:189], 1, v[188:189]
	v_lshl_add_u64 v[190:191], s[92:93], 0, v[188:189]
	v_lshl_add_u64 v[192:193], s[10:11], 0, v[188:189]
	global_load_dwordx4 v[188:191], v[190:191], off
	s_nop 0
	global_load_dwordx4 v[192:195], v[192:193], off
	v_lshlrev_b32_e32 v1, 16, v245
	v_rcp_f32_e32 v140, v1
	v_and_b32_e32 v1, 0xffff0000, v245
	v_rcp_f32_e32 v141, v1
	v_lshlrev_b32_e32 v132, 16, v241
	v_and_b32_e32 v133, 0xffff0000, v241
	v_lshlrev_b32_e32 v1, 16, v246
	v_pk_mul_f32 v[132:133], v[140:141], v[132:133]
	v_rcp_f32_e32 v140, v1
	v_and_b32_e32 v1, 0xffff0000, v246
	v_rcp_f32_e32 v141, v1
	v_lshlrev_b32_e32 v1, 16, v247
	v_rcp_f32_e32 v142, v1
	v_and_b32_e32 v1, 0xffff0000, v247
	v_rcp_f32_e32 v143, v1
	v_lshlrev_b32_e32 v134, 16, v243
	v_and_b32_e32 v135, 0xffff0000, v243
	v_pk_mul_f32 v[72:73], v[72:73], v[2:3]
	v_pk_mul_f32 v[134:135], v[142:143], v[134:135]
	v_pk_mul_f32 v[74:75], v[74:75], v[132:133]
	v_pk_mul_f32 v[70:71], v[70:71], v[134:135]
	v_pk_mul_f32 v[140:141], v[140:141], v[196:197]
	s_waitcnt vmcnt(5)
	v_lshlrev_b32_e32 v132, 16, v248
	s_waitcnt vmcnt(4)
	v_lshlrev_b32_e32 v1, 16, v252
	v_rcp_f32_e32 v2, v1
	v_and_b32_e32 v1, 0xffff0000, v252
	v_rcp_f32_e32 v3, v1
	v_lshlrev_b32_e32 v1, 16, v253
	v_rcp_f32_e32 v134, v1
	v_and_b32_e32 v1, 0xffff0000, v253
	v_rcp_f32_e32 v135, v1
	v_and_b32_e32 v133, 0xffff0000, v248
	v_pk_mul_f32 v[2:3], v[2:3], v[132:133]
	v_lshlrev_b32_e32 v132, 16, v249
	v_and_b32_e32 v133, 0xffff0000, v249
	v_lshlrev_b32_e32 v1, 16, v254
	v_pk_mul_f32 v[68:69], v[68:69], v[140:141]
	v_pk_mul_f32 v[140:141], v[134:135], v[132:133]
	v_rcp_f32_e32 v132, v1
	v_and_b32_e32 v1, 0xffff0000, v254
	v_rcp_f32_e32 v133, v1
	v_lshlrev_b32_e32 v1, 16, v255
	v_rcp_f32_e32 v142, v1
	v_and_b32_e32 v1, 0xffff0000, v255
	v_rcp_f32_e32 v143, v1
	v_lshlrev_b32_e32 v134, 16, v250
	v_and_b32_e32 v135, 0xffff0000, v250
	v_pk_mul_f32 v[180:181], v[132:133], v[134:135]
	v_lshlrev_b32_e32 v132, 16, v251
	v_and_b32_e32 v133, 0xffff0000, v251
	v_pk_mul_f32 v[142:143], v[142:143], v[132:133]
	v_lshl_add_u64 v[132:133], v[198:199], 0, s[6:7]
	v_lshlrev_b64 v[132:133], 1, v[132:133]
	v_pk_mul_f32 v[64:65], v[64:65], v[2:3]
	v_lshl_add_u64 v[134:135], s[92:93], 0, v[132:133]
	v_lshl_add_u64 v[176:177], s[10:11], 0, v[132:133]
	global_load_dwordx4 v[132:135], v[134:135], off
	s_nop 0
	global_load_dwordx4 v[176:179], v[176:177], off
	v_pk_mul_f32 v[62:63], v[62:63], v[142:143]
	v_pk_mul_f32 v[66:67], v[66:67], v[140:141]
	v_pk_mul_f32 v[60:61], v[60:61], v[180:181]
	s_waitcnt vmcnt(5)
	v_lshlrev_b32_e32 v140, 16, v136
	s_waitcnt vmcnt(4)
	v_lshlrev_b32_e32 v1, 16, v184
	v_rcp_f32_e32 v2, v1
	v_and_b32_e32 v1, 0xffff0000, v184
	v_rcp_f32_e32 v3, v1
	v_lshlrev_b32_e32 v1, 16, v185
	v_rcp_f32_e32 v142, v1
	v_and_b32_e32 v1, 0xffff0000, v185
	v_and_b32_e32 v141, 0xffff0000, v136
	v_rcp_f32_e32 v143, v1
	v_lshlrev_b32_e32 v1, 16, v186
	v_pk_mul_f32 v[2:3], v[2:3], v[140:141]
	v_rcp_f32_e32 v140, v1
	v_and_b32_e32 v1, 0xffff0000, v186
	v_rcp_f32_e32 v141, v1
	v_lshlrev_b32_e32 v1, 16, v187
	v_rcp_f32_e32 v180, v1
	v_and_b32_e32 v1, 0xffff0000, v187
	v_lshlrev_b32_e32 v136, 16, v137
	v_and_b32_e32 v137, 0xffff0000, v137
	v_rcp_f32_e32 v181, v1
	s_waitcnt vmcnt(2)
; __device__ __forceinline__ float rcp_f(float x) { return __builtin_amdgcn_rcpf(x); }
;     __device__ __forceinline__ void mid(AccT& acc, const pg8::Unit& u, int wr, int wc, int fr, int fq) const {
; #pragma unroll
;         for (int ai = 0; ai < 2; ++ai)
; #pragma unroll
;             for (int m = 0; m < 4; ++m) { int row = u.pm * 256 + ai * 128 + wr * 64 + m * 16 + fr; if (row >= M) row = M - 1;
; #pragma unroll
;                 for (int bj = 0; bj < 2; ++bj) { const size_t o = (size_t)row * D + u.pn * 256 + bj * 128 + wc * 32 + 8 * fq;
;                     const u32x4 a = *(const u32x4*)(mga + o), b = *(const u32x4*)(mgb + o);
;                     f32x4 r0, r1;
;                     r0[0] = bflo(a.x) * rcp_f(bflo(b.x)); r0[1] = bfhi(a.x) * rcp_f(bfhi(b.x)); r0[2] = bflo(a.y) * rcp_f(bflo(b.y)); r0[3] = bfhi(a.y) * rcp_f(bfhi(b.y));
;                     r1[0] = bflo(a.z) * rcp_f(bflo(b.z)); r1[1] = bfhi(a.z) * rcp_f(bfhi(b.z)); r1[2] = bflo(a.w) * rcp_f(bflo(b.w)); r1[3] = bfhi(a.w) * rcp_f(bfhi(b.w));
;                     acc[ai][bj][m][0] = acc[ai][bj][m][0] * r0; acc[ai][bj][m][1] = acc[ai][bj][m][1] * r1; } }
;     }
	v_lshlrev_b32_e32 v1, 16, v192
	v_pk_mul_f32 v[136:137], v[142:143], v[136:137]
	v_pk_mul_f32 v[32:33], v[32:33], v[2:3]
	v_rcp_f32_e32 v2, v1
	v_add_u32_e32 v1, s27, v173
	v_pk_mul_f32 v[34:35], v[34:35], v[136:137]
	v_min_i32_e32 v136, 0x407f, v1
	v_ashrrev_i32_e32 v137, 31, v136
	v_lshlrev_b32_e32 v142, 16, v138
	v_and_b32_e32 v143, 0xffff0000, v138
	v_lshlrev_b32_e32 v138, 16, v139
	v_and_b32_e32 v139, 0xffff0000, v139
	v_lshlrev_b64 v[136:137], 10, v[136:137]
	v_pk_mul_f32 v[138:139], v[180:181], v[138:139]
	v_lshl_add_u64 v[180:181], v[136:137], 0, v[154:155]
	v_lshl_add_u64 v[136:137], v[180:181], 0, s[38:39]
	v_pk_mul_f32 v[140:141], v[140:141], v[142:143]
	v_lshlrev_b64 v[136:137], 1, v[136:137]
	v_pk_mul_f32 v[30:31], v[30:31], v[138:139]
	v_pk_mul_f32 v[28:29], v[28:29], v[140:141]
	v_lshl_add_u64 v[138:139], s[92:93], 0, v[136:137]
	v_lshl_add_u64 v[140:141], s[10:11], 0, v[136:137]
	global_load_dwordx4 v[136:139], v[138:139], off
	s_nop 0
	global_load_dwordx4 v[140:143], v[140:141], off
	v_and_b32_e32 v1, 0xffff0000, v192
	v_rcp_f32_e32 v3, v1
	v_lshlrev_b32_e32 v1, 16, v193
	v_rcp_f32_e32 v184, v1
	v_and_b32_e32 v1, 0xffff0000, v193
	v_rcp_f32_e32 v185, v1
	v_lshlrev_b32_e32 v182, 16, v188
	v_and_b32_e32 v183, 0xffff0000, v188
	v_pk_mul_f32 v[2:3], v[2:3], v[182:183]
	v_lshlrev_b32_e32 v182, 16, v189
	v_and_b32_e32 v183, 0xffff0000, v189
	v_lshlrev_b32_e32 v1, 16, v194
	v_pk_mul_f32 v[182:183], v[184:185], v[182:183]
	v_rcp_f32_e32 v184, v1
	v_and_b32_e32 v1, 0xffff0000, v194
	v_rcp_f32_e32 v185, v1
	v_lshlrev_b32_e32 v1, 16, v195
	v_rcp_f32_e32 v188, v1
	v_and_b32_e32 v1, 0xffff0000, v195
	v_rcp_f32_e32 v189, v1
	v_lshlrev_b32_e32 v186, 16, v190
	v_and_b32_e32 v187, 0xffff0000, v190
	v_pk_mul_f32 v[56:57], v[56:57], v[2:3]
	v_lshl_add_u64 v[180:181], v[180:181], 0, s[6:7]
	v_pk_mul_f32 v[184:185], v[184:185], v[186:187]
	v_lshlrev_b32_e32 v186, 16, v191
	v_and_b32_e32 v187, 0xffff0000, v191
	v_lshlrev_b64 v[180:181], 1, v[180:181]
	v_pk_mul_f32 v[186:187], v[188:189], v[186:187]
	v_pk_mul_f32 v[58:59], v[58:59], v[182:183]
	v_pk_mul_f32 v[52:53], v[52:53], v[184:185]
	s_waitcnt vmcnt(2)
	v_lshlrev_b32_e32 v1, 16, v176
	v_rcp_f32_e32 v2, v1
	v_and_b32_e32 v1, 0xffff0000, v176
	v_rcp_f32_e32 v3, v1
	v_lshlrev_b32_e32 v1, 16, v177
	v_lshl_add_u64 v[182:183], s[92:93], 0, v[180:181]
	v_lshl_add_u64 v[184:185], s[10:11], 0, v[180:181]
	v_rcp_f32_e32 v176, v1
	v_and_b32_e32 v1, 0xffff0000, v177
	v_pk_mul_f32 v[54:55], v[54:55], v[186:187]
	global_load_dwordx4 v[180:183], v[182:183], off
	s_nop 0
	global_load_dwordx4 v[184:187], v[184:185], off
	v_rcp_f32_e32 v177, v1
	v_lshlrev_b32_e32 v188, 16, v132
	v_and_b32_e32 v189, 0xffff0000, v132
	v_lshlrev_b32_e32 v132, 16, v133
	v_and_b32_e32 v133, 0xffff0000, v133
	v_lshlrev_b32_e32 v194, 16, v134
	v_and_b32_e32 v195, 0xffff0000, v134
	v_add_u32_e32 v134, s27, v174
	v_pk_mul_f32 v[132:133], v[176:177], v[132:133]
	v_min_i32_e32 v176, 0x407f, v134
	v_lshlrev_b32_e32 v1, 16, v178
	v_ashrrev_i32_e32 v177, 31, v176
	v_rcp_f32_e32 v192, v1
	v_and_b32_e32 v1, 0xffff0000, v178
	v_lshlrev_b64 v[176:177], 10, v[176:177]
	v_rcp_f32_e32 v193, v1
	v_lshlrev_b32_e32 v1, 16, v179
	v_lshl_add_u64 v[198:199], v[176:177], 0, v[154:155]
	v_rcp_f32_e32 v196, v1
	v_and_b32_e32 v1, 0xffff0000, v179
	v_lshl_add_u64 v[176:177], v[198:199], 0, s[38:39]
	v_lshlrev_b64 v[176:177], 1, v[176:177]
	v_rcp_f32_e32 v197, v1
	v_pk_mul_f32 v[2:3], v[2:3], v[188:189]
	v_lshl_add_u64 v[178:179], s[92:93], 0, v[176:177]
	v_lshl_add_u64 v[188:189], s[10:11], 0, v[176:177]
	global_load_dwordx4 v[176:179], v[178:179], off
	s_nop 0
	global_load_dwordx4 v[188:191], v[188:189], off
	v_lshlrev_b32_e32 v134, 16, v135
	v_and_b32_e32 v135, 0xffff0000, v135
	v_pk_mul_f32 v[24:25], v[24:25], v[2:3]
	v_pk_mul_f32 v[134:135], v[196:197], v[134:135]
	v_pk_mul_f32 v[26:27], v[26:27], v[132:133]
	v_pk_mul_f32 v[22:23], v[22:23], v[134:135]
	v_pk_mul_f32 v[192:193], v[192:193], v[194:195]
	s_waitcnt vmcnt(5)
	v_lshlrev_b32_e32 v132, 16, v136
	s_waitcnt vmcnt(4)
; __device__ __forceinline__ float rcp_f(float x) { return __builtin_amdgcn_rcpf(x); }
;     __device__ __forceinline__ void mid(AccT& acc, const pg8::Unit& u, int wr, int wc, int fr, int fq) const {
; #pragma unroll
;         for (int ai = 0; ai < 2; ++ai)
; #pragma unroll
;             for (int m = 0; m < 4; ++m) { int row = u.pm * 256 + ai * 128 + wr * 64 + m * 16 + fr; if (row >= M) row = M - 1;
; #pragma unroll
;                 for (int bj = 0; bj < 2; ++bj) { const size_t o = (size_t)row * D + u.pn * 256 + bj * 128 + wc * 32 + 8 * fq;
;                     const u32x4 a = *(const u32x4*)(mga + o), b = *(const u32x4*)(mgb + o);
;                     f32x4 r0, r1;
;                     r0[0] = bflo(a.x) * rcp_f(bflo(b.x)); r0[1] = bfhi(a.x) * rcp_f(bfhi(b.x)); r0[2] = bflo(a.y) * rcp_f(bflo(b.y)); r0[3] = bfhi(a.y) * rcp_f(bfhi(b.y));
;                     r1[0] = bflo(a.z) * rcp_f(bflo(b.z)); r1[1] = bfhi(a.z) * rcp_f(bfhi(b.z)); r1[2] = bflo(a.w) * rcp_f(bflo(b.w)); r1[3] = bfhi(a.w) * rcp_f(bfhi(b.w));
;                     acc[ai][bj][m][0] = acc[ai][bj][m][0] * r0; acc[ai][bj][m][1] = acc[ai][bj][m][1] * r1; } }
;     }
	v_lshlrev_b32_e32 v1, 16, v140
	v_rcp_f32_e32 v2, v1
	v_and_b32_e32 v1, 0xffff0000, v140
	v_rcp_f32_e32 v3, v1
	v_lshlrev_b32_e32 v1, 16, v141
	v_rcp_f32_e32 v134, v1
	v_and_b32_e32 v1, 0xffff0000, v141
	v_rcp_f32_e32 v135, v1
	v_and_b32_e32 v133, 0xffff0000, v136
	v_pk_mul_f32 v[2:3], v[2:3], v[132:133]
	v_lshlrev_b32_e32 v132, 16, v137
	v_and_b32_e32 v133, 0xffff0000, v137
	v_pk_mul_f32 v[136:137], v[134:135], v[132:133]
	v_lshl_add_u64 v[132:133], v[198:199], 0, s[6:7]
	v_lshlrev_b64 v[132:133], 1, v[132:133]
	v_pk_mul_f32 v[20:21], v[20:21], v[192:193]
	v_lshl_add_u64 v[134:135], s[92:93], 0, v[132:133]
	v_lshl_add_u64 v[192:193], s[10:11], 0, v[132:133]
	global_load_dwordx4 v[132:135], v[134:135], off
	s_nop 0
	global_load_dwordx4 v[192:195], v[192:193], off
	v_lshlrev_b32_e32 v1, 16, v142
	v_rcp_f32_e32 v140, v1
	v_and_b32_e32 v1, 0xffff0000, v142
	v_rcp_f32_e32 v141, v1
	v_lshlrev_b32_e32 v1, 16, v143
	v_rcp_f32_e32 v142, v1
	v_and_b32_e32 v1, 0xffff0000, v143
	v_rcp_f32_e32 v143, v1
	v_lshlrev_b32_e32 v196, 16, v138
	v_and_b32_e32 v197, 0xffff0000, v138
	v_lshlrev_b32_e32 v138, 16, v139
	v_and_b32_e32 v139, 0xffff0000, v139
	v_pk_mul_f32 v[48:49], v[48:49], v[2:3]
	v_pk_mul_f32 v[138:139], v[142:143], v[138:139]
	v_pk_mul_f32 v[50:51], v[50:51], v[136:137]
	v_pk_mul_f32 v[46:47], v[46:47], v[138:139]
	v_pk_mul_f32 v[140:141], v[140:141], v[196:197]
	s_waitcnt vmcnt(5)
	v_lshlrev_b32_e32 v136, 16, v180
	s_waitcnt vmcnt(4)
	v_lshlrev_b32_e32 v1, 16, v184
	v_rcp_f32_e32 v2, v1
	v_and_b32_e32 v1, 0xffff0000, v184
	v_rcp_f32_e32 v3, v1
	v_lshlrev_b32_e32 v1, 16, v185
	v_rcp_f32_e32 v138, v1
	v_and_b32_e32 v1, 0xffff0000, v185
	v_rcp_f32_e32 v139, v1
	v_and_b32_e32 v137, 0xffff0000, v180
	v_pk_mul_f32 v[2:3], v[2:3], v[136:137]
	v_lshlrev_b32_e32 v136, 16, v181
	v_and_b32_e32 v137, 0xffff0000, v181
	v_lshlrev_b32_e32 v1, 16, v186
	v_pk_mul_f32 v[136:137], v[138:139], v[136:137]
	v_rcp_f32_e32 v138, v1
	v_and_b32_e32 v1, 0xffff0000, v186
	v_rcp_f32_e32 v139, v1
	v_lshlrev_b32_e32 v1, 16, v187
	v_rcp_f32_e32 v142, v1
	v_and_b32_e32 v1, 0xffff0000, v187
	v_rcp_f32_e32 v143, v1
	v_pk_mul_f32 v[44:45], v[44:45], v[140:141]
	v_lshlrev_b32_e32 v140, 16, v182
	v_and_b32_e32 v141, 0xffff0000, v182
	v_pk_mul_f32 v[16:17], v[16:17], v[2:3]
	v_pk_mul_f32 v[138:139], v[138:139], v[140:141]
	v_pk_mul_f32 v[18:19], v[18:19], v[136:137]
	s_waitcnt vmcnt(2)
	v_lshlrev_b32_e32 v1, 16, v188
	v_rcp_f32_e32 v2, v1
	v_and_b32_e32 v1, 0xffff0000, v188
	v_rcp_f32_e32 v3, v1
	v_lshlrev_b32_e32 v1, 16, v189
	v_pk_mul_f32 v[12:13], v[12:13], v[138:139]
	v_rcp_f32_e32 v138, v1
	v_and_b32_e32 v1, 0xffff0000, v189
	v_rcp_f32_e32 v139, v1
	v_lshlrev_b32_e32 v136, 16, v176
	v_and_b32_e32 v137, 0xffff0000, v176
	v_pk_mul_f32 v[2:3], v[2:3], v[136:137]
	v_lshlrev_b32_e32 v136, 16, v177
	v_and_b32_e32 v137, 0xffff0000, v177
	v_lshlrev_b32_e32 v1, 16, v190
	v_pk_mul_f32 v[136:137], v[138:139], v[136:137]
	v_rcp_f32_e32 v138, v1
	v_and_b32_e32 v1, 0xffff0000, v190
	v_lshlrev_b32_e32 v140, 16, v183
	v_and_b32_e32 v141, 0xffff0000, v183
	v_rcp_f32_e32 v139, v1
	v_lshlrev_b32_e32 v1, 16, v191
	v_pk_mul_f32 v[140:141], v[142:143], v[140:141]
	v_rcp_f32_e32 v142, v1
	v_and_b32_e32 v1, 0xffff0000, v191
	v_rcp_f32_e32 v143, v1
	v_pk_mul_f32 v[40:41], v[40:41], v[2:3]
	v_pk_mul_f32 v[14:15], v[14:15], v[140:141]
	v_lshlrev_b32_e32 v140, 16, v178
	s_waitcnt vmcnt(0)
	v_lshlrev_b32_e32 v1, 16, v192
	v_rcp_f32_e32 v2, v1
	v_and_b32_e32 v1, 0xffff0000, v192
	v_and_b32_e32 v141, 0xffff0000, v178
	v_rcp_f32_e32 v3, v1
	v_pk_mul_f32 v[138:139], v[138:139], v[140:141]
	v_lshlrev_b32_e32 v1, 16, v193
	v_pk_mul_f32 v[36:37], v[36:37], v[138:139]
	v_rcp_f32_e32 v138, v1
	v_and_b32_e32 v1, 0xffff0000, v193
	v_pk_mul_f32 v[42:43], v[42:43], v[136:137]
	v_lshlrev_b32_e32 v136, 16, v132
	v_and_b32_e32 v137, 0xffff0000, v132
	v_rcp_f32_e32 v139, v1
	v_lshlrev_b32_e32 v1, 16, v194
	v_lshlrev_b32_e32 v140, 16, v179
	v_and_b32_e32 v141, 0xffff0000, v179
	v_pk_mul_f32 v[2:3], v[2:3], v[136:137]
	v_rcp_f32_e32 v136, v1
	v_and_b32_e32 v1, 0xffff0000, v194
	v_pk_mul_f32 v[140:141], v[142:143], v[140:141]
	v_rcp_f32_e32 v137, v1
	v_lshlrev_b32_e32 v1, 16, v195
	v_pk_mul_f32 v[38:39], v[38:39], v[140:141]
	v_rcp_f32_e32 v140, v1
	v_and_b32_e32 v1, 0xffff0000, v195
	v_rcp_f32_e32 v141, v1
	v_lshlrev_b32_e32 v132, 16, v133
	v_and_b32_e32 v133, 0xffff0000, v133
	v_pk_mul_f32 v[132:133], v[138:139], v[132:133]
	v_lshlrev_b32_e32 v138, 16, v134
	v_and_b32_e32 v139, 0xffff0000, v134
	v_lshlrev_b32_e32 v134, 16, v135
	v_and_b32_e32 v135, 0xffff0000, v135
	v_pk_mul_f32 v[136:137], v[136:137], v[138:139]
	v_pk_mul_f32 v[134:135], v[140:141], v[134:135]
	v_pk_mul_f32 v[10:11], v[10:11], v[132:133]
	v_pk_mul_f32 v[8:9], v[8:9], v[2:3]
	v_pk_mul_f32 v[6:7], v[6:7], v[134:135]
	v_pk_mul_f32 v[4:5], v[4:5], v[136:137]
	s_waitcnt vmcnt(0)
